# attention units: Q-fragment loads issued together (4 round trips -> 1) at 4 sites; DIFF key-norm loops issue their 8 loads per iteration together with counted vmcnt
# speedup vs baseline: 1.0091x; 1.0091x over previous
.LBB0_198:
	s_cmp_gt_i32 s16, 2
	s_mov_b64 s[4:5], -1
	s_cbranch_scc0 .LBB0_309
	s_lshl_b32 s23, s28, 2
	s_lshl_b32 s14, s28, 8
	s_or_b32 s30, s23, 3
	s_mul_i32 s5, s27, 0x1800000
	v_readlane_b32 s6, v255, 11
	s_mul_hi_i32 s4, s27, 0x1800000
	v_readlane_b32 s7, v255, 12
	s_add_u32 s6, s6, s5
	s_addc_u32 s7, s7, s4
	s_lshl_b32 s4, s29, 3
	s_sub_i32 s4, 0xffffffd8, s4
	v_cvt_f32_i32_e32 v0, s4
	s_mov_b32 s8, 0x41400000
	v_mov_b32_e32 v198, v241
	v_mov_b32_e32 v11, v241
	v_div_scale_f32 v1, s[4:5], s8, s8, v0
	v_rcp_f32_e32 v2, v1
	s_mov_b32 s4, 0xc2fc0000
	v_fma_f32 v3, -v1, v2, 1.0
	v_fmac_f32_e32 v2, v3, v2
	v_div_scale_f32 v3, vcc, v0, s8, v0
	v_mul_f32_e32 v4, v3, v2
	v_fma_f32 v5, -v1, v4, v3
	v_fmac_f32_e32 v4, v5, v2
	v_fma_f32 v1, -v1, v4, v3
	v_div_fmas_f32 v1, v1, v2, v4
	v_div_fixup_f32 v0, v1, s8, v0
	v_cmp_gt_f32_e32 vcc, s4, v0
	s_and_b64 s[4:5], vcc, exec
	s_cselect_b32 s4, 0xffffffc0, 0
	v_cndmask_b32_e32 v1, 0, v238, vcc
	v_add_f32_e32 v0, v0, v1
	v_exp_f32_e32 v0, v0
	v_and_b32_e32 v14, 31, v11
	v_bfe_u32 v8, v11, 5, 1
	s_movk_i32 s8, 0x3000
	v_ldexp_f32 v0, v0, s4
	s_lshl_b32 s4, s29, 7
	s_add_u32 s4, s6, s4
	s_addc_u32 s5, s7, 0
	s_add_u32 s6, s4, 0x2400
	s_addc_u32 s7, s5, 0
	s_add_u32 s90, s4, 0x2800
	s_addc_u32 s91, s5, 0
	s_add_u32 s92, s4, 0x2c00
	s_addc_u32 s93, s5, 0
	v_readfirstlane_b32 s5, v11
	s_ashr_i32 s4, s5, 6
	s_lshl_b32 s31, s4, 5
	s_add_i32 s31, s31, s14
	v_mul_f32_e32 v192, 0x3fb8aa3b, v0
	v_or_b32_e32 v199, s31, v14
	v_mov_b64_e32 v[0:1], s[6:7]
	v_mad_i64_i32 v[0:1], s[6:7], v199, s8, v[0:1]
	v_lshlrev_b32_e32 v128, 4, v8
	v_lshl_add_u64 v[0:1], v[0:1], 0, v[128:129]
	global_load_dwordx4 v[2:5], v[0:1], off
	global_load_dwordx4 v[16:19], v[0:1], off offset:32
	global_load_dwordx4 v[20:23], v[0:1], off offset:64
	global_load_dwordx4 v[24:27], v[0:1], off offset:96
	s_mov_b32 s6, 0x3e38aa3b
	v_and_b32_e32 v10, 63, v11
	s_ashr_i32 s26, s5, 7
	v_lshlrev_b32_e32 v200, 2, v8
	v_readfirstlane_b32 s15, v198
	v_xor_b32_e32 v203, 0x80000000, v192
	s_waitcnt vmcnt(3)
	v_and_b32_e32 v7, 0xffff0000, v2
	v_lshlrev_b32_e32 v6, 16, v2
	v_pk_mul_f32 v[6:7], v[6:7], s[6:7] op_sel_hi:[1,0]
	s_nop 0
	v_cvt_pk_bf16_f32 v144, v6, v7
	v_and_b32_e32 v7, 0xffff0000, v3
	v_lshlrev_b32_e32 v6, 16, v3
	v_pk_mul_f32 v[2:3], v[6:7], s[6:7] op_sel_hi:[1,0]
	s_nop 0
	v_cvt_pk_bf16_f32 v145, v2, v3
	v_and_b32_e32 v3, 0xffff0000, v4
	v_lshlrev_b32_e32 v2, 16, v4
	v_pk_mul_f32 v[2:3], v[2:3], s[6:7] op_sel_hi:[1,0]
	s_nop 0
	v_cvt_pk_bf16_f32 v146, v2, v3
	v_and_b32_e32 v3, 0xffff0000, v5
	v_lshlrev_b32_e32 v2, 16, v5
	v_pk_mul_f32 v[2:3], v[2:3], s[6:7] op_sel_hi:[1,0]
	s_nop 0
	v_cvt_pk_bf16_f32 v147, v2, v3
	s_waitcnt vmcnt(2)
	v_and_b32_e32 v7, 0xffff0000, v16
	v_lshlrev_b32_e32 v6, 16, v16
	v_pk_mul_f32 v[6:7], v[6:7], s[6:7] op_sel_hi:[1,0]
	s_nop 0
	v_cvt_pk_bf16_f32 v148, v6, v7
	v_and_b32_e32 v7, 0xffff0000, v17
	v_lshlrev_b32_e32 v6, 16, v17
	v_pk_mul_f32 v[2:3], v[6:7], s[6:7] op_sel_hi:[1,0]
	s_nop 0
	v_cvt_pk_bf16_f32 v149, v2, v3
	v_and_b32_e32 v3, 0xffff0000, v18
	v_lshlrev_b32_e32 v2, 16, v18
	v_pk_mul_f32 v[2:3], v[2:3], s[6:7] op_sel_hi:[1,0]
	s_nop 0
	v_cvt_pk_bf16_f32 v150, v2, v3
	v_and_b32_e32 v3, 0xffff0000, v19
	v_lshlrev_b32_e32 v2, 16, v19
	v_pk_mul_f32 v[2:3], v[2:3], s[6:7] op_sel_hi:[1,0]
	s_nop 0
	v_cvt_pk_bf16_f32 v151, v2, v3
	s_waitcnt vmcnt(1)
	v_and_b32_e32 v7, 0xffff0000, v20
	v_lshlrev_b32_e32 v6, 16, v20
	v_pk_mul_f32 v[6:7], v[6:7], s[6:7] op_sel_hi:[1,0]
	s_nop 0
	v_cvt_pk_bf16_f32 v152, v6, v7
	v_and_b32_e32 v7, 0xffff0000, v21
	v_lshlrev_b32_e32 v6, 16, v21
	v_pk_mul_f32 v[2:3], v[6:7], s[6:7] op_sel_hi:[1,0]
	s_nop 0
	v_cvt_pk_bf16_f32 v153, v2, v3
	v_and_b32_e32 v3, 0xffff0000, v22
	v_lshlrev_b32_e32 v2, 16, v22
	v_pk_mul_f32 v[2:3], v[2:3], s[6:7] op_sel_hi:[1,0]
	s_nop 0
	v_cvt_pk_bf16_f32 v154, v2, v3
	v_and_b32_e32 v3, 0xffff0000, v23
	v_lshlrev_b32_e32 v2, 16, v23
	v_pk_mul_f32 v[2:3], v[2:3], s[6:7] op_sel_hi:[1,0]
	s_nop 0
	v_cvt_pk_bf16_f32 v155, v2, v3
	s_waitcnt vmcnt(0)
	v_and_b32_e32 v5, 0xffff0000, v24
	v_lshlrev_b32_e32 v4, 16, v24
	v_pk_mul_f32 v[4:5], v[4:5], s[6:7] op_sel_hi:[1,0]
	s_nop 0
	v_cvt_pk_bf16_f32 v156, v4, v5
	v_and_b32_e32 v5, 0xffff0000, v25
	v_lshlrev_b32_e32 v4, 16, v25
	v_pk_mul_f32 v[0:1], v[4:5], s[6:7] op_sel_hi:[1,0]
	v_lshlrev_b32_e32 v4, 1, v11
	v_cvt_pk_bf16_f32 v157, v0, v1
	v_and_b32_e32 v1, 0xffff0000, v26
	v_lshlrev_b32_e32 v0, 16, v26
	v_pk_mul_f32 v[0:1], v[0:1], s[6:7] op_sel_hi:[1,0]
	s_nop 0
	v_cvt_pk_bf16_f32 v158, v0, v1
	v_and_b32_e32 v1, 0xffff0000, v27
	v_lshlrev_b32_e32 v0, 16, v27
	v_mul_u32_u24_e32 v3, 0x3000, v10
	v_pk_mul_f32 v[0:1], v[0:1], s[6:7] op_sel_hi:[1,0]
	v_lshl_add_u32 v12, s4, 4, v3
	v_and_b32_e32 v3, 51, v11
	v_cvt_pk_bf16_f32 v159, v0, v1
	v_lshlrev_b32_e32 v0, 4, v11
	v_and_or_b32 v3, v4, 8, v3
	v_ashrrev_i32_e32 v1, 3, v11
	v_lshlrev_b32_e32 v3, 1, v3
	v_and_b32_e32 v4, 8, v11
	v_and_b32_e32 v0, 0x70, v0
	s_mulk_i32 s4, 0x480
	s_movk_i32 s6, 0x90
	v_mul_lo_u32 v2, v1, s8
	v_or3_b32 v15, v3, v4, s4
	v_mad_u64_u32 v[8:9], s[4:5], v1, s6, v[0:1]
	v_or_b32_e32 v13, v0, v2
	s_mul_i32 s4, s30, 0xc0000
	v_add_u32_e32 v0, s4, v13
	global_load_dwordx4 v[4:7], v0, s[90:91]
	v_add_u32_e32 v9, s4, v12
	s_mul_i32 s4, s28, 0x300000
	v_add_u32_e32 v16, s4, v13
	s_add_i32 s5, s4, 0x180000
	v_add_u32_e32 v16, 0xc0000, v16
	global_load_dwordx4 v[160:163], v16, s[90:91]
	v_add_u32_e32 v0, s5, v13
	v_add_u32_e32 v201, 0, v8
	global_load_dwordx4 v[0:3], v0, s[90:91]
	v_add_u32_e32 v16, s5, v12
	global_load_dwordx4 v[164:167], v16, s[92:93]
	v_add_u32_e32 v202, 0, v15
	s_cmp_gt_i32 s26, 2
	s_waitcnt vmcnt(3)
	ds_write_b128 v201, v[4:7]
	global_load_dwordx4 v[4:7], v9, s[92:93]
	s_waitcnt vmcnt(0)
	ds_write_b16 v202, v4 offset:18432
	ds_write_b16_d16_hi v202, v4 offset:18576
	ds_write_b16 v202, v5 offset:18720
	ds_write_b16_d16_hi v202, v5 offset:18864
	ds_write_b16 v202, v6 offset:19008
	ds_write_b16_d16_hi v202, v6 offset:19152
	ds_write_b16 v202, v7 offset:19296
	ds_write_b16_d16_hi v202, v7 offset:19440
	v_mad_u32_u24 v4, v14, s6, v128
	v_add_u32_e32 v204, 0, v4
	ds_write_b128 v201, v[0:3] offset:9216
	s_waitcnt lgkmcnt(0)
	s_barrier
	s_cbranch_scc0 .LBB0_204
	v_lshl_or_b32 v0, s30, 6, v200
	v_sub_u32_e32 v0, v199, v0
	v_cvt_f32_i32_e32 v1, v0
	s_mov_b32 s4, 2.0
	s_mov_b32 s5, 0x40400000
	v_mul_f32_e64 v0, -v192, v1
	v_pk_fma_f32 v[34:35], v[192:193], s[4:5], v[0:1] op_sel_hi:[0,1,0]
	s_mov_b32 s4, 0x41000000
	s_mov_b32 s5, 0x41100000
	v_pk_fma_f32 v[36:37], v[192:193], s[4:5], v[0:1] op_sel_hi:[0,1,0]
	s_mov_b32 s4, 0x41200000
	s_mov_b32 s5, 0x41300000
	v_pk_fma_f32 v[38:39], v[192:193], s[4:5], v[0:1] op_sel_hi:[0,1,0]
	s_mov_b32 s4, 0x41800000
	s_mov_b32 s5, 0x41880000
	v_pk_fma_f32 v[40:41], v[192:193], s[4:5], v[0:1] op_sel_hi:[0,1,0]
	s_mov_b32 s4, 0x41900000
	s_mov_b32 s5, 0x41980000
	v_pk_fma_f32 v[42:43], v[192:193], s[4:5], v[0:1] op_sel_hi:[0,1,0]
	s_mov_b32 s4, 0x41c00000
	s_mov_b32 s5, 0x41c80000
	v_pk_fma_f32 v[44:45], v[192:193], s[4:5], v[0:1] op_sel_hi:[0,1,0]
	s_mov_b32 s4, 0x41d00000
	s_mov_b32 s5, 0x41d80000
	v_pk_fma_f32 v[46:47], v[192:193], s[4:5], v[0:1] op_sel_hi:[0,1,0]
	s_mov_b32 s4, 0x42680000
	s_mov_b32 s5, 0x426c0000
	v_pk_fma_f32 v[62:63], v[192:193], s[4:5], v[0:1] op_sel_hi:[0,1,0]
	s_mov_b32 s4, 0x42600000
	s_mov_b32 s5, 0x42640000
	v_pk_fma_f32 v[60:61], v[192:193], s[4:5], v[0:1] op_sel_hi:[0,1,0]
	s_mov_b32 s4, 0x42480000
	s_mov_b32 s5, 0x424c0000
	v_pk_fma_f32 v[58:59], v[192:193], s[4:5], v[0:1] op_sel_hi:[0,1,0]
	s_mov_b32 s4, 0x42400000
	s_mov_b32 s5, 0x42440000
	v_pk_fma_f32 v[56:57], v[192:193], s[4:5], v[0:1] op_sel_hi:[0,1,0]
	s_mov_b32 s4, 0x42280000
	s_mov_b32 s5, 0x422c0000
	v_pk_fma_f32 v[54:55], v[192:193], s[4:5], v[0:1] op_sel_hi:[0,1,0]
	s_mov_b32 s4, 0x42200000
	s_mov_b32 s5, 0x42240000
	v_pk_fma_f32 v[52:53], v[192:193], s[4:5], v[0:1] op_sel_hi:[0,1,0]
	s_mov_b32 s4, 0x42080000
	s_mov_b32 s5, 0x420c0000
	v_pk_fma_f32 v[50:51], v[192:193], s[4:5], v[0:1] op_sel_hi:[0,1,0]
	s_mov_b32 s4, 0x42000000
	s_mov_b32 s5, 0x42040000
	v_fma_f32 v33, -v192, v1, v192
	v_mov_b32_e32 v32, v0
	v_pk_fma_f32 v[48:49], v[192:193], s[4:5], v[0:1] op_sel_hi:[0,1,0]
	ds_read_b128 v[0:3], v204
	ds_read_b128 v[4:7], v204 offset:32
	v_fmac_f32_e32 v32, 0, v192
	s_waitcnt lgkmcnt(1)
	s_nop 0
	v_mfma_f32_32x32x16_bf16 v[32:47], v[0:3], v[144:147], v[32:47]
	ds_read_b128 v[0:3], v204 offset:4608
	s_waitcnt lgkmcnt(0)
	v_mfma_f32_32x32x16_bf16 v[48:63], v[0:3], v[144:147], v[48:63]
	ds_read_b128 v[0:3], v204 offset:4640
	s_waitcnt lgkmcnt(0)
	v_mfma_f32_32x32x16_bf16 v[48:63], v[0:3], v[148:151], v[48:63]
	ds_read_b128 v[0:3], v204 offset:64
	v_mfma_f32_32x32x16_bf16 v[32:47], v[4:7], v[148:151], v[32:47]
	s_waitcnt lgkmcnt(0)
	v_mfma_f32_32x32x16_bf16 v[32:47], v[0:3], v[152:155], v[32:47]
	ds_read_b128 v[0:3], v204 offset:4672
	s_waitcnt lgkmcnt(0)
	v_mfma_f32_32x32x16_bf16 v[48:63], v[0:3], v[152:155], v[48:63]
	ds_read_b128 v[0:3], v204 offset:96
	s_waitcnt lgkmcnt(0)
	v_mfma_f32_32x32x16_bf16 v[32:47], v[0:3], v[156:159], v[32:47]
	ds_read_b128 v[0:3], v204 offset:4704
	s_waitcnt lgkmcnt(0)
	v_mfma_f32_32x32x16_bf16 v[48:63], v[0:3], v[156:159], v[48:63]
	v_mov_b64_e32 v[194:195], v[192:193]
	s_lshl_b32 s22, s29, 6
	s_cbranch_execz .LBB0_205
	s_branch .LBB0_206

.LBB0_309:
	s_mov_b64 s[66:67], 0
	s_and_b64 vcc, exec, s[4:5]
	s_mov_b64 s[4:5], 0
	s_cbranch_vccz .LBB0_357
	s_mul_i32 s25, s27, 0x1800000
	v_readlane_b32 s4, v255, 11
	s_mul_hi_i32 s19, s27, 0x1800000
	v_readlane_b32 s5, v255, 12
	s_add_u32 s11, s4, s25
	s_addc_u32 s14, s5, s19
	s_lshl_b32 s26, s29, 8
	s_add_u32 s4, s11, s26
	v_mov_b32_e32 v202, v241
	s_addc_u32 s5, s14, 0
	v_mov_b32_e32 v4, v241
	s_add_u32 s64, s4, 0x1800
	s_addc_u32 s65, s5, 0
	v_readfirstlane_b32 s10, v4
	s_ashr_i32 s9, s10, 6
	s_lshl_b32 s30, s28, 8
	s_lshl_b32 s8, s9, 5
	v_and_b32_e32 v2, 31, v4
	s_add_i32 s21, s8, s30
	v_bfe_u32 v3, v4, 5, 1
	v_or_b32_e32 v5, s21, v2
	v_mov_b64_e32 v[0:1], s[64:65]
	s_movk_i32 s4, 0x3000
	v_mad_i64_i32 v[0:1], s[4:5], v5, s4, v[0:1]
	v_lshlrev_b32_e32 v128, 4, v3
	v_lshl_add_u64 v[0:1], v[0:1], 0, v[128:129]
	global_load_dwordx4 v[6:9], v[0:1], off
	global_load_dwordx4 v[16:19], v[0:1], off offset:32
	global_load_dwordx4 v[20:23], v[0:1], off offset:64
	global_load_dwordx4 v[24:27], v[0:1], off offset:96
	s_mov_b32 s4, 0x3e38aa3b
	s_add_i32 s15, s28, 1
	s_lshl_b32 s23, s15, 8
	v_readfirstlane_b32 s17, v202
	v_cmp_gt_i32_e32 vcc, s23, v4
	s_waitcnt vmcnt(3)
	v_and_b32_e32 v11, 0xffff0000, v6
	v_lshlrev_b32_e32 v10, 16, v6
	v_pk_mul_f32 v[10:11], v[10:11], s[4:5] op_sel_hi:[1,0]
	s_nop 0
	v_cvt_pk_bf16_f32 v96, v10, v11
	v_and_b32_e32 v11, 0xffff0000, v7
	v_lshlrev_b32_e32 v10, 16, v7
	v_pk_mul_f32 v[6:7], v[10:11], s[4:5] op_sel_hi:[1,0]
	s_nop 0
	v_cvt_pk_bf16_f32 v97, v6, v7
	v_and_b32_e32 v7, 0xffff0000, v8
	v_lshlrev_b32_e32 v6, 16, v8
	v_pk_mul_f32 v[6:7], v[6:7], s[4:5] op_sel_hi:[1,0]
	s_nop 0
	v_cvt_pk_bf16_f32 v98, v6, v7
	v_and_b32_e32 v7, 0xffff0000, v9
	v_lshlrev_b32_e32 v6, 16, v9
	v_pk_mul_f32 v[6:7], v[6:7], s[4:5] op_sel_hi:[1,0]
	s_nop 0
	v_cvt_pk_bf16_f32 v99, v6, v7
	s_waitcnt vmcnt(2)
	v_and_b32_e32 v11, 0xffff0000, v16
	v_lshlrev_b32_e32 v10, 16, v16
	v_pk_mul_f32 v[10:11], v[10:11], s[4:5] op_sel_hi:[1,0]
	s_nop 0
	v_cvt_pk_bf16_f32 v100, v10, v11
	v_and_b32_e32 v11, 0xffff0000, v17
	v_lshlrev_b32_e32 v10, 16, v17
	v_pk_mul_f32 v[6:7], v[10:11], s[4:5] op_sel_hi:[1,0]
	s_nop 0
	v_cvt_pk_bf16_f32 v101, v6, v7
	v_and_b32_e32 v7, 0xffff0000, v18
	v_lshlrev_b32_e32 v6, 16, v18
	v_pk_mul_f32 v[6:7], v[6:7], s[4:5] op_sel_hi:[1,0]
	s_nop 0
	v_cvt_pk_bf16_f32 v102, v6, v7
	v_and_b32_e32 v7, 0xffff0000, v19
	v_lshlrev_b32_e32 v6, 16, v19
	v_pk_mul_f32 v[6:7], v[6:7], s[4:5] op_sel_hi:[1,0]
	s_nop 0
	v_cvt_pk_bf16_f32 v103, v6, v7
	s_waitcnt vmcnt(1)
	v_and_b32_e32 v11, 0xffff0000, v20
	v_lshlrev_b32_e32 v10, 16, v20
	v_pk_mul_f32 v[10:11], v[10:11], s[4:5] op_sel_hi:[1,0]
	s_nop 0
	v_cvt_pk_bf16_f32 v104, v10, v11
	v_and_b32_e32 v11, 0xffff0000, v21
	v_lshlrev_b32_e32 v10, 16, v21
	v_pk_mul_f32 v[6:7], v[10:11], s[4:5] op_sel_hi:[1,0]
	s_nop 0
	v_cvt_pk_bf16_f32 v105, v6, v7
	v_and_b32_e32 v7, 0xffff0000, v22
	v_lshlrev_b32_e32 v6, 16, v22
	v_pk_mul_f32 v[6:7], v[6:7], s[4:5] op_sel_hi:[1,0]
	s_nop 0
	v_cvt_pk_bf16_f32 v106, v6, v7
	v_and_b32_e32 v7, 0xffff0000, v23
	v_lshlrev_b32_e32 v6, 16, v23
	v_pk_mul_f32 v[6:7], v[6:7], s[4:5] op_sel_hi:[1,0]
	s_nop 0
	v_cvt_pk_bf16_f32 v107, v6, v7
	s_waitcnt vmcnt(0)
	v_and_b32_e32 v1, 0xffff0000, v24
	v_lshlrev_b32_e32 v0, 16, v24
	v_pk_mul_f32 v[0:1], v[0:1], s[4:5] op_sel_hi:[1,0]
	s_nop 0
	v_cvt_pk_bf16_f32 v108, v0, v1
	v_and_b32_e32 v1, 0xffff0000, v25
	v_lshlrev_b32_e32 v0, 16, v25
	v_pk_mul_f32 v[0:1], v[0:1], s[4:5] op_sel_hi:[1,0]
	s_nop 0
	v_cvt_pk_bf16_f32 v109, v0, v1
	v_and_b32_e32 v1, 0xffff0000, v26
	v_lshlrev_b32_e32 v0, 16, v26
	v_pk_mul_f32 v[0:1], v[0:1], s[4:5] op_sel_hi:[1,0]
	v_mov_b32_e32 v8, 0
	v_cvt_pk_bf16_f32 v110, v0, v1
	v_and_b32_e32 v1, 0xffff0000, v27
	v_lshlrev_b32_e32 v0, 16, v27
	v_pk_mul_f32 v[0:1], v[0:1], s[4:5] op_sel_hi:[1,0]
	s_nop 0
	v_cvt_pk_bf16_f32 v111, v0, v1
	v_and_b32_e32 v1, 0xffff0000, v96
	v_lshlrev_b32_e32 v0, 16, v96
	v_mul_f32_e32 v5, v1, v1
	v_fmac_f32_e32 v5, v0, v0
	v_lshlrev_b32_e32 v0, 16, v97
	v_fmac_f32_e32 v5, v0, v0
	v_and_b32_e32 v0, 0xffff0000, v97
	v_fmac_f32_e32 v5, v0, v0
	v_lshlrev_b32_e32 v0, 16, v98
	v_fmac_f32_e32 v5, v0, v0
	v_and_b32_e32 v0, 0xffff0000, v98
	v_fmac_f32_e32 v5, v0, v0
	v_lshlrev_b32_e32 v0, 16, v99
	v_fmac_f32_e32 v5, v0, v0
	v_and_b32_e32 v0, 0xffff0000, v99
	v_fmac_f32_e32 v5, v0, v0
	v_lshlrev_b32_e32 v0, 16, v100
	v_fmac_f32_e32 v5, v0, v0
	v_and_b32_e32 v0, 0xffff0000, v100
	v_fmac_f32_e32 v5, v0, v0
	v_lshlrev_b32_e32 v0, 16, v101
	v_fmac_f32_e32 v5, v0, v0
	v_and_b32_e32 v0, 0xffff0000, v101
	v_fmac_f32_e32 v5, v0, v0
	v_lshlrev_b32_e32 v0, 16, v102
	v_fmac_f32_e32 v5, v0, v0
	v_and_b32_e32 v0, 0xffff0000, v102
	v_fmac_f32_e32 v5, v0, v0
	v_lshlrev_b32_e32 v0, 16, v103
	v_fmac_f32_e32 v5, v0, v0
	v_and_b32_e32 v0, 0xffff0000, v103
	v_fmac_f32_e32 v5, v0, v0
	v_lshlrev_b32_e32 v0, 16, v104
	v_fmac_f32_e32 v5, v0, v0
	v_and_b32_e32 v0, 0xffff0000, v104
	v_fmac_f32_e32 v5, v0, v0
	v_lshlrev_b32_e32 v0, 16, v105
	v_fmac_f32_e32 v5, v0, v0
	v_and_b32_e32 v0, 0xffff0000, v105
	v_fmac_f32_e32 v5, v0, v0
	v_lshlrev_b32_e32 v0, 16, v106
	v_fmac_f32_e32 v5, v0, v0
	v_and_b32_e32 v0, 0xffff0000, v106
	v_fmac_f32_e32 v5, v0, v0
	v_lshlrev_b32_e32 v0, 16, v107
	v_fmac_f32_e32 v5, v0, v0
	v_and_b32_e32 v0, 0xffff0000, v107
	v_fmac_f32_e32 v5, v0, v0
	v_lshlrev_b32_e32 v0, 16, v108
	v_fmac_f32_e32 v5, v0, v0
	v_and_b32_e32 v0, 0xffff0000, v108
	v_fmac_f32_e32 v5, v0, v0
	v_lshlrev_b32_e32 v0, 16, v109
	v_fmac_f32_e32 v5, v0, v0
	v_and_b32_e32 v0, 0xffff0000, v109
	v_fmac_f32_e32 v5, v0, v0
	v_lshlrev_b32_e32 v0, 16, v110
	v_fmac_f32_e32 v5, v0, v0
	v_and_b32_e32 v0, 0xffff0000, v110
	v_fmac_f32_e32 v5, v0, v0
	v_lshlrev_b32_e32 v0, 16, v111
	v_fmac_f32_e32 v5, v0, v0
	v_and_b32_e32 v0, 0xffff0000, v111
	v_fmac_f32_e32 v5, v0, v0
	v_mov_b32_e32 v6, v5
	v_mov_b32_e32 v7, v5
	s_nop 1
	v_permlane32_swap_b32_e32 v6, v7
	s_and_saveexec_b64 s[4:5], vcc
	s_cbranch_execz .LBB0_314
	v_readlane_b32 s6, v255, 34
	s_add_u32 s6, s6, s26
	v_readlane_b32 s7, v255, 35
	s_addc_u32 s7, s7, 0
	s_add_u32 s6, s6, s25
	s_addc_u32 s7, s7, s19
	v_mov_b64_e32 v[0:1], s[6:7]
	s_movk_i32 s6, 0x3000
	v_mad_i64_i32 v[0:1], s[6:7], v4, s6, v[0:1]
	v_mov_b32_e32 v8, 0
	s_mov_b64 s[6:7], 0
	v_mov_b32_e32 v9, v4
.LBB0_312:
	global_load_dwordx4 v[20:23], v[0:1], off offset:-112
	global_load_dwordx4 v[24:27], v[0:1], off offset:-96
	global_load_dwordx4 v[28:31], v[0:1], off offset:-80
	global_load_dwordx4 v[32:35], v[0:1], off offset:-64
	global_load_dwordx4 v[36:39], v[0:1], off offset:-48
	global_load_dwordx4 v[40:43], v[0:1], off offset:-32
	global_load_dwordx4 v[44:47], v[0:1], off offset:-16
	global_load_dwordx4 v[48:51], v[0:1], off
	v_lshl_add_u64 v[0:1], v[0:1], 0, s[82:83]
	v_add_u32_e32 v9, 0x200, v9
	v_max_f32_e32 v8, v8, v8
	v_cmp_le_i32_e32 vcc, s23, v9
	s_or_b64 s[6:7], vcc, s[6:7]
	s_waitcnt vmcnt(7)
	v_lshlrev_b32_e32 v14, 16, v20
	v_and_b32_e32 v10, 0xffff0000, v20
	v_mul_f32_e32 v10, v10, v10
	v_fmac_f32_e32 v10, v14, v14
	v_lshlrev_b32_e32 v11, 16, v21
	v_fmac_f32_e32 v10, v11, v11
	v_and_b32_e32 v11, 0xffff0000, v21
	v_fmac_f32_e32 v10, v11, v11
	v_lshlrev_b32_e32 v11, 16, v22
	v_fmac_f32_e32 v10, v11, v11
	v_and_b32_e32 v11, 0xffff0000, v22
	v_fmac_f32_e32 v10, v11, v11
	v_lshlrev_b32_e32 v11, 16, v23
	v_fmac_f32_e32 v10, v11, v11
	v_and_b32_e32 v11, 0xffff0000, v23
	v_fmac_f32_e32 v10, v11, v11
	s_waitcnt vmcnt(6)
	v_lshlrev_b32_e32 v11, 16, v24
	v_fmac_f32_e32 v10, v11, v11
	v_and_b32_e32 v11, 0xffff0000, v24
	v_fmac_f32_e32 v10, v11, v11
	v_lshlrev_b32_e32 v11, 16, v25
	v_fmac_f32_e32 v10, v11, v11
	v_and_b32_e32 v11, 0xffff0000, v25
	v_fmac_f32_e32 v10, v11, v11
	v_lshlrev_b32_e32 v11, 16, v26
	v_fmac_f32_e32 v10, v11, v11
	v_and_b32_e32 v11, 0xffff0000, v26
	v_fmac_f32_e32 v10, v11, v11
	v_lshlrev_b32_e32 v11, 16, v27
	v_fmac_f32_e32 v10, v11, v11
	v_and_b32_e32 v11, 0xffff0000, v27
	v_fmac_f32_e32 v10, v11, v11
	s_waitcnt vmcnt(5)
	v_lshlrev_b32_e32 v11, 16, v28
	v_fmac_f32_e32 v10, v11, v11
	v_and_b32_e32 v11, 0xffff0000, v28
	v_fmac_f32_e32 v10, v11, v11
	v_lshlrev_b32_e32 v11, 16, v29
	v_fmac_f32_e32 v10, v11, v11
	v_and_b32_e32 v11, 0xffff0000, v29
	v_fmac_f32_e32 v10, v11, v11
	v_lshlrev_b32_e32 v11, 16, v30
	v_fmac_f32_e32 v10, v11, v11
	v_and_b32_e32 v11, 0xffff0000, v30
	v_fmac_f32_e32 v10, v11, v11
	v_lshlrev_b32_e32 v11, 16, v31
	v_fmac_f32_e32 v10, v11, v11
	v_and_b32_e32 v11, 0xffff0000, v31
	v_fmac_f32_e32 v10, v11, v11
	s_waitcnt vmcnt(4)
	v_lshlrev_b32_e32 v11, 16, v32
	v_fmac_f32_e32 v10, v11, v11
	v_and_b32_e32 v11, 0xffff0000, v32
	v_fmac_f32_e32 v10, v11, v11
	v_lshlrev_b32_e32 v11, 16, v33
	v_fmac_f32_e32 v10, v11, v11
	v_and_b32_e32 v11, 0xffff0000, v33
	v_fmac_f32_e32 v10, v11, v11
	v_lshlrev_b32_e32 v11, 16, v34
	v_fmac_f32_e32 v10, v11, v11
	v_and_b32_e32 v11, 0xffff0000, v34
	v_fmac_f32_e32 v10, v11, v11
	v_lshlrev_b32_e32 v11, 16, v35
	v_fmac_f32_e32 v10, v11, v11
	v_and_b32_e32 v11, 0xffff0000, v35
	v_fmac_f32_e32 v10, v11, v11
	s_waitcnt vmcnt(3)
	v_lshlrev_b32_e32 v11, 16, v36
	v_fmac_f32_e32 v10, v11, v11
	v_and_b32_e32 v11, 0xffff0000, v36
	v_fmac_f32_e32 v10, v11, v11
	v_lshlrev_b32_e32 v11, 16, v37
	v_fmac_f32_e32 v10, v11, v11
	v_and_b32_e32 v11, 0xffff0000, v37
	v_fmac_f32_e32 v10, v11, v11
	v_lshlrev_b32_e32 v11, 16, v38
	v_fmac_f32_e32 v10, v11, v11
	v_and_b32_e32 v11, 0xffff0000, v38
	v_fmac_f32_e32 v10, v11, v11
	v_lshlrev_b32_e32 v11, 16, v39
	v_fmac_f32_e32 v10, v11, v11
	v_and_b32_e32 v11, 0xffff0000, v39
	v_fmac_f32_e32 v10, v11, v11
	s_waitcnt vmcnt(2)
	v_lshlrev_b32_e32 v11, 16, v40
	v_fmac_f32_e32 v10, v11, v11
	v_and_b32_e32 v11, 0xffff0000, v40
	v_fmac_f32_e32 v10, v11, v11
	v_lshlrev_b32_e32 v11, 16, v41
	v_fmac_f32_e32 v10, v11, v11
	v_and_b32_e32 v11, 0xffff0000, v41
	v_fmac_f32_e32 v10, v11, v11
	v_lshlrev_b32_e32 v11, 16, v42
	v_fmac_f32_e32 v10, v11, v11
	v_and_b32_e32 v11, 0xffff0000, v42
	v_fmac_f32_e32 v10, v11, v11
	v_lshlrev_b32_e32 v11, 16, v43
	v_fmac_f32_e32 v10, v11, v11
	v_and_b32_e32 v11, 0xffff0000, v43
	v_fmac_f32_e32 v10, v11, v11
	s_waitcnt vmcnt(1)
	v_lshlrev_b32_e32 v11, 16, v44
	v_fmac_f32_e32 v10, v11, v11
	v_and_b32_e32 v11, 0xffff0000, v44
	v_fmac_f32_e32 v10, v11, v11
	v_lshlrev_b32_e32 v11, 16, v45
	v_fmac_f32_e32 v10, v11, v11
	v_and_b32_e32 v11, 0xffff0000, v45
	v_fmac_f32_e32 v10, v11, v11
	v_and_b32_e32 v15, 0xffff0000, v46
	v_lshlrev_b32_e32 v14, 16, v46
	v_pk_mul_f32 v[14:15], v[14:15], v[14:15]
	s_nop 0
	v_add_f32_e32 v10, v14, v10
	v_add_f32_e32 v10, v15, v10
	v_and_b32_e32 v15, 0xffff0000, v47
	v_lshlrev_b32_e32 v14, 16, v47
	v_pk_mul_f32 v[14:15], v[14:15], v[14:15]
	s_nop 0
	v_add_f32_e32 v10, v14, v10
	v_add_f32_e32 v10, v15, v10
	s_waitcnt vmcnt(0)
	v_and_b32_e32 v15, 0xffff0000, v48
	v_lshlrev_b32_e32 v14, 16, v48
	v_pk_mul_f32 v[14:15], v[14:15], v[14:15]
	s_nop 0
	v_add_f32_e32 v10, v14, v10
	v_add_f32_e32 v10, v15, v10
	v_and_b32_e32 v15, 0xffff0000, v49
	v_lshlrev_b32_e32 v14, 16, v49
	v_pk_mul_f32 v[14:15], v[14:15], v[14:15]
	s_nop 0
	v_add_f32_e32 v10, v14, v10
	v_add_f32_e32 v10, v15, v10
	v_and_b32_e32 v15, 0xffff0000, v50
	v_lshlrev_b32_e32 v14, 16, v50
	v_pk_mul_f32 v[14:15], v[14:15], v[14:15]
	s_nop 0
	v_add_f32_e32 v10, v14, v10
	v_add_f32_e32 v10, v15, v10
	v_and_b32_e32 v15, 0xffff0000, v51
	v_lshlrev_b32_e32 v14, 16, v51
	v_pk_mul_f32 v[14:15], v[14:15], v[14:15]
	s_nop 0
	v_add_f32_e32 v10, v14, v10
	v_add_f32_e32 v10, v15, v10
	v_max_f32_e32 v8, v8, v10
	s_andn2_b64 exec, exec, s[6:7]
	s_cbranch_execnz .LBB0_312
	s_or_b64 exec, exec, s[6:7]

.LBB0_333:
	v_mov_b32_e32 v68, v241
	v_mov_b64_e32 v[64:65], s[64:65]
	v_readfirstlane_b32 s10, v68
	s_ashr_i32 s9, s10, 6
	s_lshl_b32 s8, s9, 5
	v_and_b32_e32 v66, 31, v68
	s_add_i32 s21, s8, s30
	v_bfe_u32 v67, v68, 5, 1
	v_or_b32_e32 v69, s21, v66
	s_movk_i32 s4, 0x3000
	v_mad_i64_i32 v[64:65], s[4:5], v69, s4, v[64:65]
	v_lshlrev_b32_e32 v128, 4, v67
	v_lshl_add_u64 v[64:65], v[64:65], 0, v[128:129]
	global_load_dwordx4 v[70:73], v[64:65], off offset:128
	global_load_dwordx4 v[84:87], v[64:65], off offset:160
	global_load_dwordx4 v[88:91], v[64:65], off offset:192
	global_load_dwordx4 v[92:95], v[64:65], off offset:224
	s_mov_b32 s4, 0x3e38aa3b
	v_mov_b32_e32 v203, v196
	v_mov_b32_e32 v204, v196
	s_nop 1
	v_permlane32_swap_b32_e32 v203, v204
	v_cmp_gt_i32_e32 vcc, s23, v68
	s_waitcnt vmcnt(3)
	v_and_b32_e32 v75, 0xffff0000, v70
	v_lshlrev_b32_e32 v74, 16, v70
	v_pk_mul_f32 v[74:75], v[74:75], s[4:5] op_sel_hi:[1,0]
	s_nop 0
	v_cvt_pk_bf16_f32 v162, v74, v75
	v_and_b32_e32 v75, 0xffff0000, v71
	v_lshlrev_b32_e32 v74, 16, v71
	v_pk_mul_f32 v[70:71], v[74:75], s[4:5] op_sel_hi:[1,0]
	s_nop 0
	v_cvt_pk_bf16_f32 v163, v70, v71
	v_and_b32_e32 v71, 0xffff0000, v72
	v_lshlrev_b32_e32 v70, 16, v72
	v_pk_mul_f32 v[70:71], v[70:71], s[4:5] op_sel_hi:[1,0]
	s_nop 0
	v_cvt_pk_bf16_f32 v164, v70, v71
	v_and_b32_e32 v71, 0xffff0000, v73
	v_lshlrev_b32_e32 v70, 16, v73
	v_pk_mul_f32 v[70:71], v[70:71], s[4:5] op_sel_hi:[1,0]
	s_nop 0
	v_cvt_pk_bf16_f32 v165, v70, v71
	s_waitcnt vmcnt(2)
	v_and_b32_e32 v75, 0xffff0000, v84
	v_lshlrev_b32_e32 v74, 16, v84
	v_pk_mul_f32 v[74:75], v[74:75], s[4:5] op_sel_hi:[1,0]
	s_nop 0
	v_cvt_pk_bf16_f32 v166, v74, v75
	v_and_b32_e32 v75, 0xffff0000, v85
	v_lshlrev_b32_e32 v74, 16, v85
	v_pk_mul_f32 v[70:71], v[74:75], s[4:5] op_sel_hi:[1,0]
	s_nop 0
	v_cvt_pk_bf16_f32 v167, v70, v71
	v_and_b32_e32 v71, 0xffff0000, v86
	v_lshlrev_b32_e32 v70, 16, v86
	v_pk_mul_f32 v[70:71], v[70:71], s[4:5] op_sel_hi:[1,0]
	s_nop 0
	v_cvt_pk_bf16_f32 v168, v70, v71
	v_and_b32_e32 v71, 0xffff0000, v87
	v_lshlrev_b32_e32 v70, 16, v87
	v_pk_mul_f32 v[70:71], v[70:71], s[4:5] op_sel_hi:[1,0]
	s_nop 0
	v_cvt_pk_bf16_f32 v169, v70, v71
	s_waitcnt vmcnt(1)
	v_and_b32_e32 v75, 0xffff0000, v88
	v_lshlrev_b32_e32 v74, 16, v88
	v_pk_mul_f32 v[74:75], v[74:75], s[4:5] op_sel_hi:[1,0]
	s_nop 0
	v_cvt_pk_bf16_f32 v170, v74, v75
	v_and_b32_e32 v75, 0xffff0000, v89
	v_lshlrev_b32_e32 v74, 16, v89
	v_pk_mul_f32 v[70:71], v[74:75], s[4:5] op_sel_hi:[1,0]
	s_nop 0
	v_cvt_pk_bf16_f32 v171, v70, v71
	v_and_b32_e32 v71, 0xffff0000, v90
	v_lshlrev_b32_e32 v70, 16, v90
	v_pk_mul_f32 v[70:71], v[70:71], s[4:5] op_sel_hi:[1,0]
	s_nop 0
	v_cvt_pk_bf16_f32 v172, v70, v71
	v_and_b32_e32 v71, 0xffff0000, v91
	v_lshlrev_b32_e32 v70, 16, v91
	v_pk_mul_f32 v[70:71], v[70:71], s[4:5] op_sel_hi:[1,0]
	s_nop 0
	v_cvt_pk_bf16_f32 v173, v70, v71
	s_waitcnt vmcnt(0)
	v_and_b32_e32 v65, 0xffff0000, v92
	v_lshlrev_b32_e32 v64, 16, v92
	v_pk_mul_f32 v[64:65], v[64:65], s[4:5] op_sel_hi:[1,0]
	s_nop 0
	v_cvt_pk_bf16_f32 v174, v64, v65
	v_and_b32_e32 v65, 0xffff0000, v93
	v_lshlrev_b32_e32 v64, 16, v93
	v_pk_mul_f32 v[64:65], v[64:65], s[4:5] op_sel_hi:[1,0]
	s_nop 0
	v_cvt_pk_bf16_f32 v175, v64, v65
	v_and_b32_e32 v65, 0xffff0000, v94
	v_lshlrev_b32_e32 v64, 16, v94
	v_pk_mul_f32 v[64:65], v[64:65], s[4:5] op_sel_hi:[1,0]
	v_mov_b32_e32 v72, 0
	v_cvt_pk_bf16_f32 v176, v64, v65
	v_and_b32_e32 v65, 0xffff0000, v95
	v_lshlrev_b32_e32 v64, 16, v95
	v_pk_mul_f32 v[64:65], v[64:65], s[4:5] op_sel_hi:[1,0]
	s_nop 0
	v_cvt_pk_bf16_f32 v177, v64, v65
	v_and_b32_e32 v65, 0xffff0000, v162
	v_lshlrev_b32_e32 v64, 16, v162
	v_mul_f32_e32 v69, v65, v65
	v_fmac_f32_e32 v69, v64, v64
	v_lshlrev_b32_e32 v64, 16, v163
	v_fmac_f32_e32 v69, v64, v64
	v_and_b32_e32 v64, 0xffff0000, v163
	v_fmac_f32_e32 v69, v64, v64
	v_lshlrev_b32_e32 v64, 16, v164
	v_fmac_f32_e32 v69, v64, v64
	v_and_b32_e32 v64, 0xffff0000, v164
	v_fmac_f32_e32 v69, v64, v64
	v_lshlrev_b32_e32 v64, 16, v165
	v_fmac_f32_e32 v69, v64, v64
	v_and_b32_e32 v64, 0xffff0000, v165
	v_fmac_f32_e32 v69, v64, v64
	v_lshlrev_b32_e32 v64, 16, v166
	v_fmac_f32_e32 v69, v64, v64
	v_and_b32_e32 v64, 0xffff0000, v166
	v_fmac_f32_e32 v69, v64, v64
	v_lshlrev_b32_e32 v64, 16, v167
	v_fmac_f32_e32 v69, v64, v64
	v_and_b32_e32 v64, 0xffff0000, v167
	v_fmac_f32_e32 v69, v64, v64
	v_lshlrev_b32_e32 v64, 16, v168
	v_fmac_f32_e32 v69, v64, v64
	v_and_b32_e32 v64, 0xffff0000, v168
	v_fmac_f32_e32 v69, v64, v64
	v_lshlrev_b32_e32 v64, 16, v169
	v_fmac_f32_e32 v69, v64, v64
	v_and_b32_e32 v64, 0xffff0000, v169
	v_fmac_f32_e32 v69, v64, v64
	v_lshlrev_b32_e32 v64, 16, v170
	v_fmac_f32_e32 v69, v64, v64
	v_and_b32_e32 v64, 0xffff0000, v170
	v_fmac_f32_e32 v69, v64, v64
	v_lshlrev_b32_e32 v64, 16, v171
	v_fmac_f32_e32 v69, v64, v64
	v_and_b32_e32 v64, 0xffff0000, v171
	v_fmac_f32_e32 v69, v64, v64
	v_lshlrev_b32_e32 v64, 16, v172
	v_fmac_f32_e32 v69, v64, v64
	v_and_b32_e32 v64, 0xffff0000, v172
	v_fmac_f32_e32 v69, v64, v64
	v_lshlrev_b32_e32 v64, 16, v173
	v_fmac_f32_e32 v69, v64, v64
	v_and_b32_e32 v64, 0xffff0000, v173
	v_fmac_f32_e32 v69, v64, v64
	v_lshlrev_b32_e32 v64, 16, v174
	v_fmac_f32_e32 v69, v64, v64
	v_and_b32_e32 v64, 0xffff0000, v174
	v_fmac_f32_e32 v69, v64, v64
	v_lshlrev_b32_e32 v64, 16, v175
	v_fmac_f32_e32 v69, v64, v64
	v_and_b32_e32 v64, 0xffff0000, v175
	v_fmac_f32_e32 v69, v64, v64
	v_lshlrev_b32_e32 v64, 16, v176
	v_fmac_f32_e32 v69, v64, v64
	v_and_b32_e32 v64, 0xffff0000, v176
	v_fmac_f32_e32 v69, v64, v64
	v_lshlrev_b32_e32 v64, 16, v177
	v_fmac_f32_e32 v69, v64, v64
	v_and_b32_e32 v64, 0xffff0000, v177
	v_fmac_f32_e32 v69, v64, v64
	v_mov_b32_e32 v70, v69
	v_mov_b32_e32 v71, v69
	s_nop 1
	v_permlane32_swap_b32_e32 v70, v71
	s_and_saveexec_b64 s[4:5], vcc
	s_cbranch_execz .LBB0_337
	v_readlane_b32 s6, v255, 36
	s_add_u32 s6, s6, s26
	v_readlane_b32 s7, v255, 37
	s_addc_u32 s7, s7, 0
	s_add_u32 s6, s6, s25
	s_addc_u32 s7, s7, s19
	v_mov_b64_e32 v[64:65], s[6:7]
	s_movk_i32 s6, 0x3000
	v_mad_i64_i32 v[64:65], s[6:7], v68, s6, v[64:65]
	v_mov_b32_e32 v72, 0
	s_mov_b64 s[6:7], 0
	v_mov_b32_e32 v73, v68
.LBB0_335:
	global_load_dwordx4 v[96:99], v[64:65], off offset:-112
	global_load_dwordx4 v[100:103], v[64:65], off offset:-96
	global_load_dwordx4 v[104:107], v[64:65], off offset:-80
	global_load_dwordx4 v[108:111], v[64:65], off offset:-64
	global_load_dwordx4 v[112:115], v[64:65], off offset:-48
	global_load_dwordx4 v[116:119], v[64:65], off offset:-32
	global_load_dwordx4 v[120:123], v[64:65], off offset:-16
	global_load_dwordx4 v[124:127], v[64:65], off
	v_lshl_add_u64 v[64:65], v[64:65], 0, s[82:83]
	v_add_u32_e32 v73, 0x200, v73
	v_max_f32_e32 v72, v72, v72
	v_cmp_le_i32_e32 vcc, s23, v73
	s_or_b64 s[6:7], vcc, s[6:7]
	s_waitcnt vmcnt(7)
	v_lshlrev_b32_e32 v78, 16, v96
	v_and_b32_e32 v74, 0xffff0000, v96
	v_mul_f32_e32 v74, v74, v74
	v_fmac_f32_e32 v74, v78, v78
	v_lshlrev_b32_e32 v75, 16, v97
	v_fmac_f32_e32 v74, v75, v75
	v_and_b32_e32 v75, 0xffff0000, v97
	v_fmac_f32_e32 v74, v75, v75
	v_lshlrev_b32_e32 v75, 16, v98
	v_fmac_f32_e32 v74, v75, v75
	v_and_b32_e32 v75, 0xffff0000, v98
	v_fmac_f32_e32 v74, v75, v75
	v_lshlrev_b32_e32 v75, 16, v99
	v_fmac_f32_e32 v74, v75, v75
	v_and_b32_e32 v75, 0xffff0000, v99
	v_fmac_f32_e32 v74, v75, v75
	s_waitcnt vmcnt(6)
	v_lshlrev_b32_e32 v75, 16, v100
	v_fmac_f32_e32 v74, v75, v75
	v_and_b32_e32 v75, 0xffff0000, v100
	v_fmac_f32_e32 v74, v75, v75
	v_lshlrev_b32_e32 v75, 16, v101
	v_fmac_f32_e32 v74, v75, v75
	v_and_b32_e32 v75, 0xffff0000, v101
	v_fmac_f32_e32 v74, v75, v75
	v_lshlrev_b32_e32 v75, 16, v102
	v_fmac_f32_e32 v74, v75, v75
	v_and_b32_e32 v75, 0xffff0000, v102
	v_fmac_f32_e32 v74, v75, v75
	v_lshlrev_b32_e32 v75, 16, v103
	v_fmac_f32_e32 v74, v75, v75
	v_and_b32_e32 v75, 0xffff0000, v103
	v_fmac_f32_e32 v74, v75, v75
	s_waitcnt vmcnt(5)
	v_lshlrev_b32_e32 v75, 16, v104
	v_fmac_f32_e32 v74, v75, v75
	v_and_b32_e32 v75, 0xffff0000, v104
	v_fmac_f32_e32 v74, v75, v75
	v_lshlrev_b32_e32 v75, 16, v105
	v_fmac_f32_e32 v74, v75, v75
	v_and_b32_e32 v75, 0xffff0000, v105
	v_fmac_f32_e32 v74, v75, v75
	v_lshlrev_b32_e32 v75, 16, v106
	v_fmac_f32_e32 v74, v75, v75
	v_and_b32_e32 v75, 0xffff0000, v106
	v_fmac_f32_e32 v74, v75, v75
	v_lshlrev_b32_e32 v75, 16, v107
	v_fmac_f32_e32 v74, v75, v75
	v_and_b32_e32 v75, 0xffff0000, v107
	v_fmac_f32_e32 v74, v75, v75
	s_waitcnt vmcnt(4)
	v_lshlrev_b32_e32 v75, 16, v108
	v_fmac_f32_e32 v74, v75, v75
	v_and_b32_e32 v75, 0xffff0000, v108
	v_fmac_f32_e32 v74, v75, v75
	v_lshlrev_b32_e32 v75, 16, v109
	v_fmac_f32_e32 v74, v75, v75
	v_and_b32_e32 v75, 0xffff0000, v109
	v_fmac_f32_e32 v74, v75, v75
	v_lshlrev_b32_e32 v75, 16, v110
	v_fmac_f32_e32 v74, v75, v75
	v_and_b32_e32 v75, 0xffff0000, v110
	v_fmac_f32_e32 v74, v75, v75
	v_lshlrev_b32_e32 v75, 16, v111
	v_fmac_f32_e32 v74, v75, v75
	v_and_b32_e32 v75, 0xffff0000, v111
	v_fmac_f32_e32 v74, v75, v75
	s_waitcnt vmcnt(3)
	v_lshlrev_b32_e32 v75, 16, v112
	v_fmac_f32_e32 v74, v75, v75
	v_and_b32_e32 v75, 0xffff0000, v112
	v_fmac_f32_e32 v74, v75, v75
	v_lshlrev_b32_e32 v75, 16, v113
	v_fmac_f32_e32 v74, v75, v75
	v_and_b32_e32 v75, 0xffff0000, v113
	v_fmac_f32_e32 v74, v75, v75
	v_lshlrev_b32_e32 v75, 16, v114
	v_fmac_f32_e32 v74, v75, v75
	v_and_b32_e32 v75, 0xffff0000, v114
	v_fmac_f32_e32 v74, v75, v75
	v_lshlrev_b32_e32 v75, 16, v115
	v_fmac_f32_e32 v74, v75, v75
	v_and_b32_e32 v75, 0xffff0000, v115
	v_fmac_f32_e32 v74, v75, v75
	s_waitcnt vmcnt(2)
	v_lshlrev_b32_e32 v75, 16, v116
	v_fmac_f32_e32 v74, v75, v75
	v_and_b32_e32 v75, 0xffff0000, v116
	v_fmac_f32_e32 v74, v75, v75
	v_lshlrev_b32_e32 v75, 16, v117
	v_fmac_f32_e32 v74, v75, v75
	v_and_b32_e32 v75, 0xffff0000, v117
	v_fmac_f32_e32 v74, v75, v75
	v_lshlrev_b32_e32 v75, 16, v118
	v_fmac_f32_e32 v74, v75, v75
	v_and_b32_e32 v75, 0xffff0000, v118
	v_fmac_f32_e32 v74, v75, v75
	v_lshlrev_b32_e32 v75, 16, v119
	v_fmac_f32_e32 v74, v75, v75
	v_and_b32_e32 v75, 0xffff0000, v119
	v_fmac_f32_e32 v74, v75, v75
	s_waitcnt vmcnt(1)
	v_lshlrev_b32_e32 v75, 16, v120
	v_fmac_f32_e32 v74, v75, v75
	v_and_b32_e32 v75, 0xffff0000, v120
	v_fmac_f32_e32 v74, v75, v75
	v_lshlrev_b32_e32 v75, 16, v121
	v_fmac_f32_e32 v74, v75, v75
	v_and_b32_e32 v75, 0xffff0000, v121
	v_fmac_f32_e32 v74, v75, v75
	v_and_b32_e32 v79, 0xffff0000, v122
	v_lshlrev_b32_e32 v78, 16, v122
	v_pk_mul_f32 v[78:79], v[78:79], v[78:79]
	s_nop 0
	v_add_f32_e32 v74, v78, v74
	v_add_f32_e32 v74, v79, v74
	v_and_b32_e32 v79, 0xffff0000, v123
	v_lshlrev_b32_e32 v78, 16, v123
	v_pk_mul_f32 v[78:79], v[78:79], v[78:79]
	s_nop 0
	v_add_f32_e32 v74, v78, v74
	v_add_f32_e32 v74, v79, v74
	s_waitcnt vmcnt(0)
	v_and_b32_e32 v79, 0xffff0000, v124
	v_lshlrev_b32_e32 v78, 16, v124
	v_pk_mul_f32 v[78:79], v[78:79], v[78:79]
	s_nop 0
	v_add_f32_e32 v74, v78, v74
	v_add_f32_e32 v74, v79, v74
	v_and_b32_e32 v79, 0xffff0000, v125
	v_lshlrev_b32_e32 v78, 16, v125
	v_pk_mul_f32 v[78:79], v[78:79], v[78:79]
	s_nop 0
	v_add_f32_e32 v74, v78, v74
	v_add_f32_e32 v74, v79, v74
	v_and_b32_e32 v79, 0xffff0000, v126
	v_lshlrev_b32_e32 v78, 16, v126
	v_pk_mul_f32 v[78:79], v[78:79], v[78:79]
	s_nop 0
	v_add_f32_e32 v74, v78, v74
	v_add_f32_e32 v74, v79, v74
	v_and_b32_e32 v79, 0xffff0000, v127
	v_lshlrev_b32_e32 v78, 16, v127
	v_pk_mul_f32 v[78:79], v[78:79], v[78:79]
	s_nop 0
	v_add_f32_e32 v74, v78, v74
	v_add_f32_e32 v74, v79, v74
	v_max_f32_e32 v72, v72, v74
	s_andn2_b64 exec, exec, s[6:7]
	s_cbranch_execnz .LBB0_335
	s_or_b64 exec, exec, s[6:7]

.LBB0_371:
	v_readlane_b32 s4, v255, 11
	v_readlane_b32 s5, v255, 12
	s_add_u32 s4, s4, s10
	s_addc_u32 s5, s5, s9
	s_lshl_b32 s6, s29, 7
	s_add_u32 s8, s4, s6
	s_addc_u32 s9, s5, 0
	s_add_u32 s96, s8, 0x400
	v_pk_add_f32 v[2:3], v[2:3], v[4:5] op_sel_hi:[1,0]
	v_pk_add_f32 v[0:1], v[0:1], v[4:5] op_sel_hi:[1,0]
	v_lshl_add_u32 v4, v246, 4, 0
	s_addc_u32 s97, s9, 0
	v_mov_b32_e32 v8, v241
	ds_write_b128 v4, v[0:3] offset:55296
	s_waitcnt lgkmcnt(0)
	s_barrier
	s_add_u32 s36, s8, 0x800
	s_addc_u32 s37, s9, 0
	v_readfirstlane_b32 s5, v8
	s_ashr_i32 s4, s5, 6
	s_lshl_b32 s30, s28, 8
	s_lshl_b32 s6, s4, 5
	v_and_b32_e32 v34, 31, v8
	s_add_i32 s31, s6, s30
	v_bfe_u32 v35, v8, 5, 1
	v_or_b32_e32 v10, s31, v34
	v_mov_b64_e32 v[0:1], s[8:9]
	s_movk_i32 s7, 0x3000
	v_mad_i64_i32 v[0:1], s[8:9], v10, s7, v[0:1]
	v_lshlrev_b32_e32 v128, 4, v35
	v_lshl_add_u64 v[0:1], v[0:1], 0, v[128:129]
	global_load_dwordx4 v[2:5], v[0:1], off
	global_load_dwordx4 v[16:19], v[0:1], off offset:32
	global_load_dwordx4 v[20:23], v[0:1], off offset:64
	global_load_dwordx4 v[24:27], v[0:1], off offset:96
	s_mov_b32 s8, 0x3e38aa3b
	v_and_b32_e32 v33, 63, v8
	s_ashr_i32 s21, s5, 7
	s_movk_i32 s5, 0x90
	s_lshl_b32 s24, s28, 2
	s_mul_i32 s19, s28, 0x300000
	v_mov_b32_e32 v249, v241
	v_mul_u32_u24_e32 v243, 0x90, v34
	s_waitcnt vmcnt(3)
	v_and_b32_e32 v7, 0xffff0000, v2
	v_lshlrev_b32_e32 v6, 16, v2
	v_pk_mul_f32 v[6:7], v[6:7], s[8:9] op_sel_hi:[1,0]
	s_nop 0
	v_cvt_pk_bf16_f32 v192, v6, v7
	v_and_b32_e32 v7, 0xffff0000, v3
	v_lshlrev_b32_e32 v6, 16, v3
	v_pk_mul_f32 v[2:3], v[6:7], s[8:9] op_sel_hi:[1,0]
	s_nop 0
	v_cvt_pk_bf16_f32 v193, v2, v3
	v_and_b32_e32 v3, 0xffff0000, v4
	v_lshlrev_b32_e32 v2, 16, v4
	v_pk_mul_f32 v[2:3], v[2:3], s[8:9] op_sel_hi:[1,0]
	s_nop 0
	v_cvt_pk_bf16_f32 v194, v2, v3
	v_and_b32_e32 v3, 0xffff0000, v5
	v_lshlrev_b32_e32 v2, 16, v5
	v_pk_mul_f32 v[2:3], v[2:3], s[8:9] op_sel_hi:[1,0]
	s_nop 0
	v_cvt_pk_bf16_f32 v195, v2, v3
	s_waitcnt vmcnt(2)
	v_and_b32_e32 v7, 0xffff0000, v16
	v_lshlrev_b32_e32 v6, 16, v16
	v_pk_mul_f32 v[6:7], v[6:7], s[8:9] op_sel_hi:[1,0]
	s_nop 0
	v_cvt_pk_bf16_f32 v196, v6, v7
	v_and_b32_e32 v7, 0xffff0000, v17
	v_lshlrev_b32_e32 v6, 16, v17
	v_pk_mul_f32 v[2:3], v[6:7], s[8:9] op_sel_hi:[1,0]
	s_nop 0
	v_cvt_pk_bf16_f32 v197, v2, v3
	v_and_b32_e32 v3, 0xffff0000, v18
	v_lshlrev_b32_e32 v2, 16, v18
	v_pk_mul_f32 v[2:3], v[2:3], s[8:9] op_sel_hi:[1,0]
	s_nop 0
	v_cvt_pk_bf16_f32 v198, v2, v3
	v_and_b32_e32 v3, 0xffff0000, v19
	v_lshlrev_b32_e32 v2, 16, v19
	v_pk_mul_f32 v[2:3], v[2:3], s[8:9] op_sel_hi:[1,0]
	s_nop 0
	v_cvt_pk_bf16_f32 v199, v2, v3
	s_waitcnt vmcnt(1)
	v_and_b32_e32 v7, 0xffff0000, v20
	v_lshlrev_b32_e32 v6, 16, v20
	v_pk_mul_f32 v[6:7], v[6:7], s[8:9] op_sel_hi:[1,0]
	s_nop 0
	v_cvt_pk_bf16_f32 v200, v6, v7
	v_and_b32_e32 v7, 0xffff0000, v21
	v_lshlrev_b32_e32 v6, 16, v21
	v_pk_mul_f32 v[2:3], v[6:7], s[8:9] op_sel_hi:[1,0]
	s_nop 0
	v_cvt_pk_bf16_f32 v201, v2, v3
	v_and_b32_e32 v3, 0xffff0000, v22
	v_lshlrev_b32_e32 v2, 16, v22
	v_pk_mul_f32 v[2:3], v[2:3], s[8:9] op_sel_hi:[1,0]
	s_nop 0
	v_cvt_pk_bf16_f32 v202, v2, v3
	v_and_b32_e32 v3, 0xffff0000, v23
	v_lshlrev_b32_e32 v2, 16, v23
	v_pk_mul_f32 v[2:3], v[2:3], s[8:9] op_sel_hi:[1,0]
	s_nop 0
	v_cvt_pk_bf16_f32 v203, v2, v3
	s_waitcnt vmcnt(0)
	v_and_b32_e32 v5, 0xffff0000, v24
	v_lshlrev_b32_e32 v4, 16, v24
	v_pk_mul_f32 v[4:5], v[4:5], s[8:9] op_sel_hi:[1,0]
	s_nop 0
	v_cvt_pk_bf16_f32 v204, v4, v5
	v_and_b32_e32 v5, 0xffff0000, v25
	v_lshlrev_b32_e32 v4, 16, v25
	v_pk_mul_f32 v[0:1], v[4:5], s[8:9] op_sel_hi:[1,0]
	s_nop 0
	v_cvt_pk_bf16_f32 v205, v0, v1
	v_and_b32_e32 v1, 0xffff0000, v26
	v_lshlrev_b32_e32 v0, 16, v26
	v_pk_mul_f32 v[0:1], v[0:1], s[8:9] op_sel_hi:[1,0]
	v_lshlrev_b32_e32 v2, 1, v8
	v_cvt_pk_bf16_f32 v206, v0, v1
	v_and_b32_e32 v1, 0xffff0000, v27
	v_lshlrev_b32_e32 v0, 16, v27
	v_pk_mul_f32 v[0:1], v[0:1], s[8:9] op_sel_hi:[1,0]
	s_nop 0
	v_cvt_pk_bf16_f32 v207, v0, v1
	v_lshlrev_b32_e32 v1, 4, v8
	v_and_b32_e32 v32, 0x70, v1
	v_mul_u32_u24_e32 v1, 0x3000, v33
	v_lshl_add_u32 v240, s4, 4, v1
	v_and_b32_e32 v1, 51, v8
	v_ashrrev_i32_e32 v0, 3, v8
	v_and_or_b32 v1, v2, 8, v1
	v_lshlrev_b32_e32 v1, 1, v1
	v_and_b32_e32 v2, 8, v8
	v_mad_u64_u32 v[8:9], s[8:9], v0, s5, v[32:33]
	s_mulk_i32 s4, 0x480
	v_mul_lo_u32 v36, v0, s7
	v_or3_b32 v9, v1, v2, s4
	s_or_b32 s4, s24, 3
	v_or_b32_e32 v11, v32, v36
	v_lshl_add_u32 v0, v10, 2, 0
	s_mul_i32 s5, s4, 0xc0000
	ds_read_b32 v144, v0 offset:55296
	v_add_u32_e32 v0, s5, v11
	global_load_dwordx4 v[4:7], v0, s[96:97]
	v_add_u32_e32 v10, s5, v240
	s_add_i32 s5, s19, 0x180000
	v_add_u32_e32 v0, s5, v11
	v_add_u32_e32 v11, s19, v11
	v_add_u32_e32 v11, 0xc0000, v11
	global_load_dwordx4 v[208:211], v11, s[96:97]
	v_add_u32_e32 v11, s5, v240
	v_add_u32_e32 v241, 0, v8
	global_load_dwordx4 v[0:3], v0, s[96:97]
	v_add_u32_e32 v242, 0, v9
	global_load_dwordx4 v[212:215], v11, s[36:37]
	s_cmp_gt_i32 s21, 2
	s_waitcnt vmcnt(3)
	ds_write_b128 v241, v[4:7]
	global_load_dwordx4 v[4:7], v10, s[36:37]
	s_waitcnt vmcnt(0)
	ds_write_b16 v242, v4 offset:18432
	ds_write_b16_d16_hi v242, v4 offset:18576
	ds_write_b16 v242, v5 offset:18720
	ds_write_b16_d16_hi v242, v5 offset:18864
	ds_write_b16 v242, v6 offset:19008
	ds_write_b16_d16_hi v242, v6 offset:19152
	ds_write_b16 v242, v7 offset:19296
	ds_write_b16_d16_hi v242, v7 offset:19440
	ds_write_b128 v241, v[0:3] offset:9216
	s_waitcnt lgkmcnt(0)
	s_barrier
	s_cbranch_scc0 .LBB0_379
	s_lshl_b32 s4, s4, 8
	s_add_i32 s4, s4, 0
	v_add_u32_e32 v24, s4, v128
	ds_read_b128 v[0:3], v24 offset:55392
	ds_read_b128 v[16:19], v24 offset:55296
	ds_read_b128 v[4:7], v24 offset:55328
	ds_read_b128 v[8:11], v24 offset:55360
	v_add3_u32 v37, v128, v243, 0
	s_waitcnt lgkmcnt(3)
	v_sub_f32_e32 v15, v144, v3
	v_sub_f32_e32 v14, v144, v2
	v_sub_f32_e32 v13, v144, v1
	v_sub_f32_e32 v12, v144, v0
	s_waitcnt lgkmcnt(0)
	v_sub_f32_e32 v11, v144, v11
	v_sub_f32_e32 v10, v144, v10
	v_sub_f32_e32 v9, v144, v9
	v_sub_f32_e32 v8, v144, v8
	v_sub_f32_e32 v7, v144, v7
	v_sub_f32_e32 v6, v144, v6
	v_sub_f32_e32 v5, v144, v5
	v_sub_f32_e32 v4, v144, v4
	v_sub_f32_e32 v3, v144, v19
	v_sub_f32_e32 v2, v144, v18
	v_sub_f32_e32 v1, v144, v17
	v_sub_f32_e32 v0, v144, v16
	ds_read_b128 v[16:19], v24 offset:55520
	ds_read_b128 v[38:41], v24 offset:55424
	ds_read_b128 v[20:23], v24 offset:55456
	ds_read_b128 v[24:27], v24 offset:55488
	s_waitcnt lgkmcnt(3)
	v_sub_f32_e32 v31, v144, v19
	v_sub_f32_e32 v30, v144, v18
	v_sub_f32_e32 v29, v144, v17
	v_sub_f32_e32 v28, v144, v16
	s_waitcnt lgkmcnt(0)
	v_sub_f32_e32 v27, v144, v27
	v_sub_f32_e32 v26, v144, v26
	v_sub_f32_e32 v25, v144, v25
	v_sub_f32_e32 v24, v144, v24
	v_sub_f32_e32 v23, v144, v23
	v_sub_f32_e32 v22, v144, v22
	v_sub_f32_e32 v21, v144, v21
	v_sub_f32_e32 v20, v144, v20
	v_sub_f32_e32 v19, v144, v41
	v_sub_f32_e32 v18, v144, v40
	v_sub_f32_e32 v17, v144, v39
	v_sub_f32_e32 v16, v144, v38
	ds_read_b128 v[38:41], v37
	s_waitcnt lgkmcnt(0)
	v_mfma_f32_32x32x16_bf16 v[0:15], v[38:41], v[192:195], v[0:15]
	ds_read_b128 v[38:41], v37 offset:4608
	s_waitcnt lgkmcnt(0)
	v_mfma_f32_32x32x16_bf16 v[16:31], v[38:41], v[192:195], v[16:31]
	ds_read_b128 v[38:41], v37 offset:32
	s_waitcnt lgkmcnt(0)
	v_mfma_f32_32x32x16_bf16 v[0:15], v[38:41], v[196:199], v[0:15]
	ds_read_b128 v[38:41], v37 offset:4640
	s_waitcnt lgkmcnt(0)
	v_mfma_f32_32x32x16_bf16 v[16:31], v[38:41], v[196:199], v[16:31]
	ds_read_b128 v[38:41], v37 offset:64
	s_waitcnt lgkmcnt(0)
	v_mfma_f32_32x32x16_bf16 v[0:15], v[38:41], v[200:203], v[0:15]
	ds_read_b128 v[38:41], v37 offset:4672
	s_waitcnt lgkmcnt(0)
	v_mfma_f32_32x32x16_bf16 v[16:31], v[38:41], v[200:203], v[16:31]
	ds_read_b128 v[38:41], v37 offset:96
	s_waitcnt lgkmcnt(0)
	v_mfma_f32_32x32x16_bf16 v[0:15], v[38:41], v[204:207], v[0:15]
	ds_read_b128 v[38:41], v37 offset:4704
	s_waitcnt lgkmcnt(0)
	v_mfma_f32_32x32x16_bf16 v[16:31], v[38:41], v[204:207], v[16:31]
	s_cbranch_execz .LBB0_380
	s_branch .LBB0_381
